# W1: step-6 W' tiles via exchanged MFMA operands (transposed accumulator) stored straight from registers as A-fragments; LDS staging, one block barrier and the per-item final fragment pass removed
# speedup vs baseline: 1.0202x; 1.0062x over previous
.LBB0_296:
	s_or_b64 exec, exec, s[44:45]
	v_cndmask_b32_e64 v0, v244, v245, s[40:41]
	v_mov_b32_e32 v1, 0x200
	v_mov_b32_e32 v2, 0x300
	v_cndmask_b32_e64 v8, v2, v1, s[40:41]
	v_mov_b32_e32 v1, 0x900
	v_mov_b32_e32 v2, 0x800
	v_add_u32_e32 v16, 0, v0
	v_lshlrev_b32_e32 v0, 5, v190
	v_cndmask_b32_e64 v20, v1, v2, s[40:41]
	v_or_b32_e32 v1, v0, v188
	s_movk_i32 s0, 0x70
	v_bitop3_b32 v128, v0, s0, v188 bitop3:0xc8
	v_mad_u32_u24 v187, v1, s24, 0
	v_mul_u32_u24_e32 v17, 0x110, v188
	v_lshlrev_b32_e32 v21, 5, v189
	v_readlane_b32 s0, v254, 41
	v_xad_u32 v4, v128, v191, v187
	v_add3_u32 v215, v16, v21, v17
	v_add3_u32 v193, s0, v8, v21
	v_add3_u32 v235, s0, v20, v21
	s_waitcnt lgkmcnt(0)
	s_barrier
	ds_read_b128 v[0:3], v4 offset:53248
	ds_read_b128 v[4:7], v4 offset:34816
	ds_read_b128 v[8:11], v193
	ds_read_b128 v[12:15], v193 offset:16
	ds_read_b128 v[16:19], v215
	ds_read_b128 v[32:35], v235
	ds_read_b128 v[194:197], v235 offset:16
	ds_read_b128 v[20:23], v215 offset:16
	ds_read_b128 v[36:39], v215 offset:8704
	ds_read_b128 v[198:201], v215 offset:8720
	s_lshl_b32 s0, s28, 1
	s_waitcnt lgkmcnt(5)
	v_pk_mul_f32 v[24:25], v[8:9], v[16:17]
	v_pk_mul_f32 v[26:27], v[10:11], v[18:19]
	s_waitcnt lgkmcnt(1)
	v_pk_mul_f32 v[8:9], v[8:9], v[36:37]
	v_pk_mul_f32 v[10:11], v[10:11], v[38:39]
	v_cvt_pk_bf16_f32 v24, v24, v25
	v_cvt_pk_bf16_f32 v25, v26, v27
	v_pk_mul_f32 v[26:27], v[12:13], v[20:21]
	v_pk_mul_f32 v[28:29], v[14:15], v[22:23]
	v_cvt_pk_bf16_f32 v8, v8, v9
	v_cvt_pk_bf16_f32 v9, v10, v11
	s_waitcnt lgkmcnt(0)
	v_pk_mul_f32 v[10:11], v[12:13], v[198:199]
	v_pk_mul_f32 v[12:13], v[14:15], v[200:201]
	v_cvt_pk_bf16_f32 v26, v26, v27
	v_cvt_pk_bf16_f32 v27, v28, v29
	v_cvt_pk_bf16_f32 v10, v10, v11
	v_cvt_pk_bf16_f32 v11, v12, v13
	v_pk_mul_f32 v[16:17], v[32:33], v[16:17] neg_lo:[0,1] neg_hi:[0,1]
	v_pk_mul_f32 v[18:19], v[34:35], v[18:19] neg_lo:[0,1] neg_hi:[0,1]
	v_cvt_pk_bf16_f32 v16, v16, v17
	v_cvt_pk_bf16_f32 v17, v18, v19
	v_pk_mul_f32 v[18:19], v[194:195], v[20:21] neg_lo:[0,1] neg_hi:[0,1]
	v_pk_mul_f32 v[20:21], v[196:197], v[22:23] neg_lo:[0,1] neg_hi:[0,1]
	v_pk_mul_f32 v[12:13], v[32:33], v[36:37] neg_lo:[0,1] neg_hi:[0,1]
	v_pk_mul_f32 v[14:15], v[34:35], v[38:39] neg_lo:[0,1] neg_hi:[0,1]
	v_cvt_pk_bf16_f32 v18, v18, v19
	v_cvt_pk_bf16_f32 v19, v20, v21
	v_cvt_pk_bf16_f32 v12, v12, v13
	v_cvt_pk_bf16_f32 v13, v14, v15
	v_pk_mul_f32 v[14:15], v[194:195], v[198:199] neg_lo:[0,1] neg_hi:[0,1]
	v_or_b32_e32 v194, 32, v191
	v_xad_u32 v198, v128, v194, v187
	v_mfma_f32_32x32x16_bf16 v[48:63], v[24:27], v[0:3], 0
	v_cvt_pk_bf16_f32 v14, v14, v15
	s_mul_i32 s1, s28, 0x24000
	v_readlane_b32 s3, v251, 41
	s_mul_hi_i32 s2, s0, 0x12000
	s_add_u32 s0, s3, s1
	v_readlane_b32 s6, v251, 42
	s_addc_u32 s1, s6, s2
	v_mfma_f32_32x32x16_bf16 v[32:47], v[8:11], v[0:3], 0
	v_mul_f32_e64 v0, v196, -v200
	v_mul_f32_e64 v1, v197, -v201
	ds_read_b128 v[194:197], v198 offset:53248
	ds_read_b128 v[198:201], v198 offset:34816
	ds_read_b128 v[202:205], v215 offset:64
	ds_read_b128 v[206:209], v193 offset:64
	ds_read_b128 v[210:213], v193 offset:80
	ds_read_b128 v[216:219], v235 offset:64
	ds_read_b128 v[220:223], v235 offset:80
	ds_read_b128 v[224:227], v215 offset:80
	s_waitcnt lgkmcnt(4)
	v_pk_mul_f32 v[228:229], v[206:207], v[202:203]
	v_pk_mul_f32 v[230:231], v[208:209], v[204:205]
	s_waitcnt lgkmcnt(2)
	v_pk_mul_f32 v[202:203], v[216:217], v[202:203] neg_lo:[0,1] neg_hi:[0,1]
	v_pk_mul_f32 v[204:205], v[218:219], v[204:205] neg_lo:[0,1] neg_hi:[0,1]
	v_cvt_pk_bf16_f32 v228, v228, v229
	v_mfma_f32_32x32x16_bf16 v[16:31], v[4:7], v[16:19], 0
	v_cvt_pk_bf16_f32 v229, v230, v231
	s_waitcnt lgkmcnt(0)
	v_mul_f32_e64 v230, v210, v224
	v_mul_f32_e64 v231, v211, v225
	v_cvt_pk_bf16_f32 v202, v202, v203
	v_cvt_pk_bf16_f32 v203, v204, v205
	v_pk_mul_f32 v[204:205], v[220:221], v[224:225] neg_lo:[0,1] neg_hi:[0,1]
	v_pk_mul_f32 v[224:225], v[222:223], v[226:227] neg_lo:[0,1] neg_hi:[0,1]
	v_cvt_pk_bf16_f32 v204, v204, v205
	v_cvt_pk_bf16_f32 v205, v224, v225
	v_pk_mul_f32 v[232:233], v[212:213], v[226:227]
	ds_read_b128 v[224:227], v215 offset:8768
	v_mfma_f32_32x32x16_bf16 v[16:31], v[198:201], v[202:205], v[16:31]
	ds_read_b128 v[202:205], v215 offset:8784
	v_cvt_pk_bf16_f32 v15, v0, v1
	s_waitcnt lgkmcnt(1)
	v_mul_f32_e64 v206, v206, v224
	v_mul_f32_e64 v207, v207, v225
	v_pk_mul_f32 v[208:209], v[208:209], v[226:227]
	v_cvt_pk_bf16_f32 v206, v206, v207
	v_cvt_pk_bf16_f32 v207, v208, v209
	s_waitcnt lgkmcnt(0)
	v_pk_mul_f32 v[208:209], v[210:211], v[202:203]
	v_pk_mul_f32 v[210:211], v[212:213], v[204:205]
	v_cvt_pk_bf16_f32 v230, v230, v231
	v_cvt_pk_bf16_f32 v231, v232, v233
	v_cvt_pk_bf16_f32 v208, v208, v209
	v_cvt_pk_bf16_f32 v209, v210, v211
	v_mfma_f32_32x32x16_bf16 v[0:15], v[4:7], v[12:15], 0
	v_mul_f32_e64 v210, v216, -v224
	v_mul_f32_e64 v211, v217, -v225
	v_mul_f32_e64 v212, v218, -v226
	v_mul_f32_e64 v213, v219, -v227
	v_mul_f32_e64 v202, v220, -v202
	v_mul_f32_e64 v203, v221, -v203
	v_cvt_pk_bf16_f32 v210, v210, v211
	v_cvt_pk_bf16_f32 v211, v212, v213
	v_cvt_pk_bf16_f32 v212, v202, v203
	s_mov_b64 s[10:11], 0
	v_mfma_f32_32x32x16_bf16 v[48:63], v[228:231], v[194:197], v[48:63]
	v_mfma_f32_32x32x16_bf16 v[32:47], v[206:209], v[194:197], v[32:47]
	v_mul_f32_e64 v194, v222, -v204
	v_mul_f32_e64 v195, v223, -v205
	v_cvt_pk_bf16_f32 v213, v194, v195
	v_or_b32_e32 v194, 64, v191
	v_or_b32_e32 v191, 0x60, v191
	v_mfma_f32_32x32x16_bf16 v[0:15], v[198:201], v[210:213], v[0:15]
	v_xad_u32 v198, v128, v194, v187
	ds_read_b128 v[194:197], v198 offset:53248
	ds_read_b128 v[198:201], v198 offset:34816
	ds_read_b128 v[202:205], v215 offset:128
	ds_read_b128 v[206:209], v193 offset:128
	ds_read_b128 v[210:213], v193 offset:144
	ds_read_b128 v[216:219], v235 offset:128
	ds_read_b128 v[220:223], v235 offset:144
	ds_read_b128 v[224:227], v215 offset:144
	s_waitcnt lgkmcnt(4)
	v_pk_mul_f32 v[228:229], v[206:207], v[202:203]
	v_pk_mul_f32 v[230:231], v[208:209], v[204:205]
	s_waitcnt lgkmcnt(2)
	v_pk_mul_f32 v[202:203], v[216:217], v[202:203] neg_lo:[0,1] neg_hi:[0,1]
	v_pk_mul_f32 v[204:205], v[218:219], v[204:205] neg_lo:[0,1] neg_hi:[0,1]
	v_cvt_pk_bf16_f32 v228, v228, v229
	v_cvt_pk_bf16_f32 v229, v230, v231
	s_waitcnt lgkmcnt(0)
	v_pk_mul_f32 v[230:231], v[210:211], v[224:225]
	v_cvt_pk_bf16_f32 v202, v202, v203
	v_cvt_pk_bf16_f32 v203, v204, v205
	v_pk_mul_f32 v[204:205], v[220:221], v[224:225] neg_lo:[0,1] neg_hi:[0,1]
	v_pk_mul_f32 v[224:225], v[222:223], v[226:227] neg_lo:[0,1] neg_hi:[0,1]
	v_cvt_pk_bf16_f32 v204, v204, v205
	v_cvt_pk_bf16_f32 v205, v224, v225
	v_pk_mul_f32 v[232:233], v[212:213], v[226:227]
	ds_read_b128 v[224:227], v215 offset:8832
	v_mfma_f32_32x32x16_bf16 v[16:31], v[198:201], v[202:205], v[16:31]
	ds_read_b128 v[202:205], v215 offset:8848
	s_waitcnt lgkmcnt(1)
	v_mul_f32_e64 v206, v206, v224
	v_mul_f32_e64 v207, v207, v225
	v_mul_f32_e64 v208, v208, v226
	v_mul_f32_e64 v209, v209, v227
	v_cvt_pk_bf16_f32 v206, v206, v207
	v_cvt_pk_bf16_f32 v207, v208, v209
	s_waitcnt lgkmcnt(0)
	v_pk_mul_f32 v[208:209], v[210:211], v[202:203]
	v_pk_mul_f32 v[210:211], v[212:213], v[204:205]
	v_cvt_pk_bf16_f32 v230, v230, v231
	v_cvt_pk_bf16_f32 v231, v232, v233
	v_cvt_pk_bf16_f32 v208, v208, v209
	v_cvt_pk_bf16_f32 v209, v210, v211
	v_mfma_f32_32x32x16_bf16 v[48:63], v[228:231], v[194:197], v[48:63]
	v_mul_f32_e64 v210, v216, -v224
	v_mul_f32_e64 v211, v217, -v225
	v_mul_f32_e64 v212, v218, -v226
	v_mul_f32_e64 v213, v219, -v227
	v_mul_f32_e64 v202, v220, -v202
	v_mul_f32_e64 v203, v221, -v203
	v_cvt_pk_bf16_f32 v210, v210, v211
	v_cvt_pk_bf16_f32 v211, v212, v213
	v_cvt_pk_bf16_f32 v212, v202, v203
	v_xad_u32 v128, v128, v191, v187
	v_mfma_f32_32x32x16_bf16 v[32:47], v[206:209], v[194:197], v[32:47]
	v_mul_f32_e64 v194, v222, -v204
	v_mul_f32_e64 v195, v223, -v205
	v_lshlrev_b32_e32 v187, 4, v214
	v_cvt_pk_bf16_f32 v213, v194, v195
	v_lshlrev_b32_e32 v191, 6, v190
	s_nop 0
	v_mfma_f32_32x32x16_bf16 v[0:15], v[198:201], v[210:213], v[0:15]
	ds_read_b128 v[194:197], v128 offset:53248
	ds_read_b128 v[198:201], v128 offset:34816
	ds_read_b128 v[202:205], v215 offset:192
	ds_read_b128 v[206:209], v193 offset:192
	ds_read_b128 v[210:213], v193 offset:208
	ds_read_b128 v[216:219], v235 offset:192
	ds_read_b128 v[220:223], v235 offset:208
	ds_read_b128 v[224:227], v215 offset:208
	s_waitcnt lgkmcnt(4)
	v_pk_mul_f32 v[228:229], v[206:207], v[202:203]
	v_pk_mul_f32 v[230:231], v[208:209], v[204:205]
	s_waitcnt lgkmcnt(2)
	v_pk_mul_f32 v[202:203], v[216:217], v[202:203] neg_lo:[0,1] neg_hi:[0,1]
	v_pk_mul_f32 v[204:205], v[218:219], v[204:205] neg_lo:[0,1] neg_hi:[0,1]
	v_cvt_pk_bf16_f32 v228, v228, v229
	v_cvt_pk_bf16_f32 v229, v230, v231
	s_waitcnt lgkmcnt(0)
	v_pk_mul_f32 v[230:231], v[210:211], v[224:225]
	v_cvt_pk_bf16_f32 v202, v202, v203
	v_cvt_pk_bf16_f32 v203, v204, v205
	v_pk_mul_f32 v[204:205], v[220:221], v[224:225] neg_lo:[0,1] neg_hi:[0,1]
	v_pk_mul_f32 v[224:225], v[222:223], v[226:227] neg_lo:[0,1] neg_hi:[0,1]
	v_cvt_pk_bf16_f32 v204, v204, v205
	v_cvt_pk_bf16_f32 v205, v224, v225
	v_pk_mul_f32 v[232:233], v[212:213], v[226:227]
	ds_read_b128 v[224:227], v215 offset:8896
	v_mfma_f32_32x32x16_bf16 v[16:31], v[198:201], v[202:205], v[16:31]
	ds_read_b128 v[202:205], v215 offset:8912
	v_cvt_pk_bf16_f32 v230, v230, v231
	v_cvt_pk_bf16_f32 v231, v232, v233
	s_waitcnt lgkmcnt(1)
	v_mul_f32_e64 v206, v206, v224
	v_mul_f32_e64 v207, v207, v225
	v_pk_mul_f32 v[208:209], v[208:209], v[226:227]
	v_cvt_pk_bf16_f32 v206, v206, v207
	v_cvt_pk_bf16_f32 v207, v208, v209
	s_waitcnt lgkmcnt(0)
	v_pk_mul_f32 v[208:209], v[210:211], v[202:203]
	v_pk_mul_f32 v[210:211], v[212:213], v[204:205]
	v_cvt_pk_bf16_f32 v208, v208, v209
	v_cvt_pk_bf16_f32 v209, v210, v211
	v_mfma_f32_32x32x16_bf16 v[48:63], v[228:231], v[194:197], v[48:63]
	v_lshrrev_b32_e32 v128, 8, v186
	v_mul_f32_e64 v210, v216, -v224
	v_mul_f32_e64 v211, v217, -v225
	v_mul_f32_e64 v212, v218, -v226
	v_mul_f32_e64 v213, v219, -v227
	v_cvt_pk_bf16_f32 v210, v210, v211
	v_cvt_pk_bf16_f32 v211, v212, v213
	v_lshlrev_b32_e32 v193, 1, v188
	v_pk_mul_f32 v[202:203], v[220:221], v[202:203] neg_lo:[0,1] neg_hi:[0,1]
	v_mfma_f32_32x32x16_bf16 v[32:47], v[206:209], v[194:197], v[32:47]
	v_mul_f32_e64 v194, v222, -v204
	v_mul_f32_e64 v195, v223, -v205
	v_cvt_pk_bf16_f32 v48, v48, v49
	v_cvt_pk_bf16_f32 v213, v194, v195
	v_mul_hi_i32_i24_e32 v195, 0x12000, v128
	v_mul_i32_i24_e32 v194, 0x12000, v128
	v_mov_b32_e32 v128, 0x1e800
	v_cndmask_b32_e64 v128, v128, v243, s[40:41]
	v_add_u32_e32 v128, 0, v128
	v_lshl_add_u64 v[194:195], s[0:1], 0, v[194:195]
	v_add3_u32 v193, v128, v191, v193
	v_lshl_or_b32 v128, v190, 11, v187
	v_cvt_pk_bf16_f32 v49, v50, v51
	v_cvt_pk_bf16_f32 v50, v52, v53
	v_lshl_add_u64 v[52:53], v[194:195], 0, v[128:129]
	s_mov_b64 s[0:1], 0xe000
	v_cvt_pk_bf16_f32 v51, v54, v55
	v_lshl_add_u64 v[54:55], v[52:53], 0, s[0:1]
	s_mov_b32 s0, 0xe000
	v_add_co_u32_e32 v190, vcc, s0, v52
	s_nop 0
	v_addc_co_u32_e32 v191, vcc, 0, v53, vcc
	global_store_dwordx4 v[190:191], v[48:51], off nt
	s_movk_i32 s0, 0x440
	v_cvt_pk_bf16_f32 v212, v202, v203
	v_cvt_pk_bf16_f32 v48, v56, v57
	v_cvt_pk_bf16_f32 v49, v58, v59
	v_cvt_pk_bf16_f32 v50, v60, v61
	v_cvt_pk_bf16_f32 v51, v62, v63
	global_store_dwordx4 v[54:55], v[48:51], off offset:1024 nt
	v_mfma_f32_32x32x16_bf16 v[0:15], v[198:201], v[210:213], v[0:15]
	v_ashrrev_i32_e32 v187, 31, v186
	s_mov_b32 s0, 0x10000
	v_add_co_u32_e32 v60, vcc, s0, v52
	v_cvt_pk_bf16_f32 v56, v32, v33
	v_cvt_pk_bf16_f32 v57, v34, v35
	v_cvt_pk_bf16_f32 v58, v36, v37
	v_cvt_pk_bf16_f32 v59, v38, v39
	v_addc_co_u32_e32 v61, vcc, 0, v53, vcc
	global_store_dwordx4 v[60:61], v[56:59], off nt
	s_nop 1
	v_cvt_pk_bf16_f32 v56, v40, v41
	v_cvt_pk_bf16_f32 v57, v42, v43
	v_cvt_pk_bf16_f32 v58, v44, v45
	v_cvt_pk_bf16_f32 v59, v46, v47
	global_store_dwordx4 v[60:61], v[56:59], off offset:1024 nt
	s_nop 1
	v_cvt_pk_bf16_f32 v16, v16, v17
	v_cvt_pk_bf16_f32 v17, v18, v19
	v_cvt_pk_bf16_f32 v18, v20, v21
	v_cvt_pk_bf16_f32 v19, v22, v23
	global_store_dwordx4 v[52:53], v[16:19], off nt
	v_cvt_pk_bf16_f32 v20, v24, v25
	v_cvt_pk_bf16_f32 v21, v26, v27
	v_cvt_pk_bf16_f32 v22, v28, v29
	v_cvt_pk_bf16_f32 v23, v30, v31
	global_store_dwordx4 v[52:53], v[20:23], off offset:1024 nt
	s_mov_b64 s[0:1], 0x2000
	v_lshl_add_u64 v[62:63], v[52:53], 0, s[0:1]
	v_cvt_pk_bf16_f32 v0, v0, v1
	v_cvt_pk_bf16_f32 v1, v2, v3
	v_cvt_pk_bf16_f32 v2, v4, v5
	v_cvt_pk_bf16_f32 v3, v6, v7
	global_store_dwordx4 v[62:63], v[0:3], off nt
	v_cvt_pk_bf16_f32 v4, v8, v9
	v_cvt_pk_bf16_f32 v5, v10, v11
	v_cvt_pk_bf16_f32 v6, v12, v13
	v_cvt_pk_bf16_f32 v7, v14, v15
	global_store_dwordx4 v[62:63], v[4:7], off offset:1024 nt
	s_waitcnt lgkmcnt(0)
	s_branch .LBB0_190
